# NA tile: bias table reads issued in the middle of the QK block; masked value from one constant register (31 fewer v_mov per tile)
# speedup vs baseline: 1.0011x; 1.0011x over previous
; template <bool DIFF>
; __device__ __forceinline__ void qkt(f32x16& a, f32x16& b, const char* Ks, const char* Qs, int krow, int r32, int hi) {
;   a = f32x16{}; b = f32x16{};
; #pragma unroll
;   for (int d = 0; d < 4; ++d) {
;     const int cb0 = (d * 16 + hi * 8) * 2, cb1 = ((d + 4) * 16 + hi * 8) * 2;
;     const bf16x8 k0 = *reinterpret_cast<const bf16x8*>(Ks + KSWZ(krow, cb0)), q0 = *reinterpret_cast<const bf16x8*>(Qs + KSWZ(r32, cb0));
;     const bf16x8 k1 = *reinterpret_cast<const bf16x8*>(Ks + KSWZ(krow, cb1)), q1 = *reinterpret_cast<const bf16x8*>(Qs + KSWZ(r32, cb1));
;     a = __builtin_amdgcn_mfma_f32_32x32x16_bf16(k0, q0, a, 0, 0, 0);
;     b = __builtin_amdgcn_mfma_f32_32x32x16_bf16(k1, q1, b, 0, 0, 0); }
;   if (!DIFF) {
; #pragma unroll
;     for (int r = 0; r < 16; ++r) a[r] += b[r]; }
; }
.LBB0_369:
	v_cmp_ge_u32_e32 vcc, s40, v159
	v_cmp_lt_u32_e64 s[40:41], s40, v160
	s_and_b64 s[88:89], vcc, s[40:41]
	s_and_saveexec_b64 s[40:41], s[88:89]
	s_cbranch_execz .LBB0_439
	v_add_u32_e32 v78, v161, v162
	ds_read_b128 v[66:69], v78
	ds_read_b128 v[70:73], v175 offset:36864
	v_add_u32_e32 v79, v161, v163
	ds_read_b128 v[74:77], v79
	ds_read_b128 v[82:85], v176 offset:36864
	v_add_u32_e32 v153, v161, v164
	v_add_u32_e32 v185, v161, v165
	s_waitcnt lgkmcnt(2)
	v_mfma_f32_32x32x16_bf16 v[98:113], v[66:69], v[70:73], 0
	ds_read_b128 v[66:69], v153
	ds_read_b128 v[186:189], v177 offset:36864
	v_add_u32_e32 v206, v161, v166
	v_add_u32_e32 v207, v161, v167
	v_add_u32_e32 v209, v161, v168
	v_add_u32_e32 v222, v161, v169
	s_waitcnt lgkmcnt(2)
	v_mfma_f32_32x32x16_bf16 v[114:129], v[74:77], v[82:85], 0
	ds_read_b128 v[74:77], v185
	ds_read_b128 v[190:193], v178 offset:36864
	s_waitcnt lgkmcnt(2)
	v_mfma_f32_32x32x16_bf16 v[98:113], v[66:69], v[186:189], v[98:113]
	ds_read_b128 v[66:69], v206
	ds_read_b128 v[194:197], v179 offset:36864
	s_waitcnt lgkmcnt(2)
	v_mfma_f32_32x32x16_bf16 v[114:129], v[74:77], v[190:193], v[114:129]
	ds_read_b128 v[74:77], v207
	ds_read_b128 v[198:201], v180 offset:36864
	s_waitcnt lgkmcnt(2)
	v_mfma_f32_32x32x16_bf16 v[98:113], v[66:69], v[194:197], v[98:113]
	ds_read_b128 v[66:69], v209
	ds_read_b128 v[202:205], v181 offset:36864
	s_waitcnt lgkmcnt(2)
	v_mfma_f32_32x32x16_bf16 v[114:129], v[74:77], v[198:201], v[114:129]
	ds_read_b128 v[74:77], v222
	ds_read_b128 v[210:213], v182 offset:36864
	s_waitcnt lgkmcnt(2)
	v_mfma_f32_32x32x16_bf16 v[98:113], v[66:69], v[202:205], v[98:113]
	ds_read_b32 v223, v170
	ds_read_b32 v224, v170 offset:4
	ds_read_b32 v225, v170 offset:8
	ds_read_b32 v226, v170 offset:12
	ds_read_b32 v227, v170 offset:32
	ds_read_b32 v228, v170 offset:36
	ds_read_b32 v229, v170 offset:40
	ds_read_b32 v230, v170 offset:44
	ds_read_b32 v231, v170 offset:64
	ds_read_b32 v232, v170 offset:68
	ds_read_b32 v233, v170 offset:72
	ds_read_b32 v234, v170 offset:76
	ds_read_b32 v235, v170 offset:96
	ds_read_b32 v236, v170 offset:100
	ds_read_b32 v237, v170 offset:104
	ds_read_b32 v238, v170 offset:108
	ds_read_b32 v239, v170 offset:128
	ds_read_b32 v240, v170 offset:132
	ds_read_b32 v241, v170 offset:136
	ds_read_b32 v242, v170 offset:140
	ds_read_b32 v243, v170 offset:160
	ds_read_b32 v244, v170 offset:164
	ds_read_b32 v245, v170 offset:168
	ds_read_b32 v246, v170 offset:172
	ds_read_b32 v247, v170 offset:192
	ds_read_b32 v248, v170 offset:196
	ds_read_b32 v249, v170 offset:200
	ds_read_b32 v250, v170 offset:204
	ds_read_b32 v251, v170 offset:224
	ds_read_b32 v252, v170 offset:228
	ds_read_b32 v253, v170 offset:232
	ds_read_b32 v254, v170 offset:236
	ds_read_b128 v[66:69], v78 offset:8192
	ds_read_b128 v[86:89], v79 offset:8192
	ds_read_b128 v[214:217], v153 offset:8192
	ds_read_b128 v[218:221], v185 offset:8192
	s_waitcnt lgkmcnt(4)
	v_mfma_f32_32x32x16_bf16 v[114:129], v[74:77], v[210:213], v[114:129]
	s_waitcnt lgkmcnt(3)
	v_mfma_f32_32x32x16_bf16 v[66:81], v[66:69], v[70:73], 0
	s_waitcnt lgkmcnt(2)
	v_mfma_f32_32x32x16_bf16 v[82:97], v[86:89], v[82:85], 0
	s_waitcnt lgkmcnt(1)
	v_mfma_f32_32x32x16_bf16 v[66:81], v[214:217], v[186:189], v[66:81]
	s_waitcnt lgkmcnt(0)
	v_mfma_f32_32x32x16_bf16 v[82:97], v[218:221], v[190:193], v[82:97]
	ds_read_b128 v[186:189], v206 offset:8192
	ds_read_b128 v[190:193], v207 offset:8192
	s_waitcnt lgkmcnt(1)
	v_mfma_f32_32x32x16_bf16 v[66:81], v[186:189], v[194:197], v[66:81]
	s_waitcnt lgkmcnt(0)
	v_mfma_f32_32x32x16_bf16 v[82:97], v[190:193], v[198:201], v[82:97]
	ds_read_b128 v[186:189], v209 offset:8192
	ds_read_b128 v[190:193], v222 offset:8192
	s_waitcnt lgkmcnt(1)
	v_mfma_f32_32x32x16_bf16 v[66:81], v[186:189], v[202:205], v[66:81]
	s_waitcnt lgkmcnt(0)
	v_mfma_f32_32x32x16_bf16 v[82:97], v[190:193], v[210:213], v[82:97]
	v_mov_b32_e32 v209, 0xf149f2ca
	v_add_f32_e32 v98, v98, v114
	s_waitcnt lgkmcnt(15)
	v_add_f32_e32 v98, v98, v223
	v_cndmask_b32_e64 v185, v209, v98, s[4:5]
	v_add_f32_e32 v98, v99, v115
	s_waitcnt lgkmcnt(15)
	v_add_f32_e32 v98, v98, v224
	v_cndmask_b32_e64 v153, v209, v98, s[6:7]
	v_add_f32_e32 v100, v100, v116
	s_waitcnt lgkmcnt(15)
	v_add_f32_e32 v100, v100, v225
	v_cndmask_b32_e64 v99, v209, v100, s[8:9]
	v_add_f32_e32 v100, v101, v117
	s_waitcnt lgkmcnt(15)
	v_add_f32_e32 v100, v100, v226
	v_cndmask_b32_e64 v98, v209, v100, s[10:11]
	v_add_f32_e32 v102, v102, v118
	s_waitcnt lgkmcnt(15)
	v_add_f32_e32 v102, v102, v227
	v_cndmask_b32_e64 v101, v209, v102, s[12:13]
	v_add_f32_e32 v102, v103, v119
	s_waitcnt lgkmcnt(15)
; __device__ __forceinline__ int crow(int r, int hi) { return (r & 3) + 8 * (r >> 2) + 4 * hi; }
; template <bool DIFF> ...
;     ...
;         BIAS_APPLY(t, 0, a0, b0, cb0); BIAS_APPLY(t, 1, a1, b1, cb1);
;         float mx = a0[0];
; #pragma unroll
;         for (int r = 1; r < 16; ++r) mx = fmaxf(mx, a0[r]);
; #pragma unroll
;         for (int r = 0; r < 16; ++r) mx = fmaxf(mx, a1[r]);
;         { auto rr = __builtin_amdgcn_permlane32_swap(__float_as_uint(mx), __float_as_uint(mx), false, false); mx = fmaxf(__uint_as_float(rr[0]), __uint_as_float(rr[1])); }
;         const float mn = fmaxf(m1, mx), alpha = __builtin_amdgcn_exp2f((m1 - mn) * C), x1 = -mn * C; m1 = mn;
;         float ps = 0.f;
; #pragma unroll
;         for (int r = 0; r < 16; ++r) { a0[r] = __builtin_amdgcn_exp2f(fmaf(a0[r], C, x1)); ps += a0[r]; }
; #pragma unroll
;         for (int r = 0; r < 16; ++r) { a1[r] = __builtin_amdgcn_exp2f(fmaf(a1[r], C, x1)); ps += a1[r]; }
;         l1 = l1 * alpha + ps;
;         if (__any(alpha < 1.0f)) {
;           if (hi == 0) wsc[r32] = alpha;
;           asm volatile("s_waitcnt lgkmcnt(0)" ::: "memory");
; #pragma unroll
;           for (int r = 0; r < 16; ++r) { const float al = wsc[crow(r, hi)];
	v_add_f32_e32 v102, v102, v228
	v_cndmask_b32_e64 v100, v209, v102, s[14:15]
	v_add_f32_e32 v104, v104, v120
	s_waitcnt lgkmcnt(15)
	v_add_f32_e32 v104, v104, v229
	v_cndmask_b32_e64 v103, v209, v104, s[16:17]
	v_add_f32_e32 v104, v105, v121
	s_waitcnt lgkmcnt(15)
	v_add_f32_e32 v104, v104, v230
	v_cndmask_b32_e64 v102, v209, v104, s[18:19]
	v_add_f32_e32 v106, v106, v122
	s_waitcnt lgkmcnt(15)
	v_add_f32_e32 v106, v106, v231
	v_cndmask_b32_e64 v105, v209, v106, s[54:55]
	v_add_f32_e32 v106, v107, v123
	s_waitcnt lgkmcnt(15)
	v_add_f32_e32 v106, v106, v232
	v_cndmask_b32_e64 v104, v209, v106, s[56:57]
	v_add_f32_e32 v108, v108, v124
	s_waitcnt lgkmcnt(15)
	v_add_f32_e32 v108, v108, v233
	v_cndmask_b32_e64 v107, v209, v108, s[58:59]
	v_add_f32_e32 v108, v109, v125
	s_waitcnt lgkmcnt(15)
	v_add_f32_e32 v108, v108, v234
	v_cndmask_b32_e64 v106, v209, v108, s[60:61]
	v_add_f32_e32 v110, v110, v126
	s_waitcnt lgkmcnt(15)
	v_add_f32_e32 v110, v110, v235
	v_cndmask_b32_e64 v109, v209, v110, s[62:63]
	v_add_f32_e32 v110, v111, v127
	s_waitcnt lgkmcnt(15)
	v_add_f32_e32 v110, v110, v236
	v_cndmask_b32_e64 v108, v209, v110, s[64:65]
	v_add_f32_e32 v112, v112, v128
	s_waitcnt lgkmcnt(15)
	v_add_f32_e32 v112, v112, v237
	v_cndmask_b32_e64 v111, v209, v112, s[66:67]
	v_add_f32_e32 v112, v113, v129
	s_waitcnt lgkmcnt(15)
	v_add_f32_e32 v112, v112, v238
	v_cndmask_b32_e64 v110, v209, v112, s[68:69]
	v_add_f32_e32 v66, v66, v82
	s_waitcnt lgkmcnt(15)
	v_add_f32_e32 v66, v66, v239
	v_cndmask_b32_e64 v113, v209, v66, s[70:71]
	v_add_f32_e32 v66, v67, v83
	s_waitcnt lgkmcnt(14)
	v_add_f32_e32 v66, v66, v240
	v_cndmask_b32_e64 v112, v209, v66, s[72:73]
	v_add_f32_e32 v68, v68, v84
	s_waitcnt lgkmcnt(13)
	v_add_f32_e32 v68, v68, v241
	v_cndmask_b32_e64 v67, v209, v68, s[74:75]
	v_add_f32_e32 v68, v69, v85
	s_waitcnt lgkmcnt(12)
	v_add_f32_e32 v68, v68, v242
	v_cndmask_b32_e64 v66, v209, v68, s[76:77]
	v_add_f32_e32 v68, v70, v86
	s_waitcnt lgkmcnt(11)
	v_add_f32_e32 v68, v68, v243
	v_cndmask_b32_e64 v82, v209, v68, s[78:79]
	v_add_f32_e32 v68, v71, v87
	s_waitcnt lgkmcnt(10)
	v_add_f32_e32 v68, v68, v244
	v_cndmask_b32_e64 v69, v209, v68, s[80:81]
	v_add_f32_e32 v68, v72, v88
	s_waitcnt lgkmcnt(9)
	v_add_f32_e32 v68, v68, v245
	v_cndmask_b32_e64 v71, v209, v68, s[82:83]
	v_add_f32_e32 v68, v73, v89
	s_waitcnt lgkmcnt(8)
	v_add_f32_e32 v68, v68, v246
	v_cndmask_b32_e64 v70, v209, v68, s[84:85]
	v_add_f32_e32 v68, v74, v90
	s_waitcnt lgkmcnt(7)
	v_add_f32_e32 v68, v68, v247
	v_cndmask_b32_e64 v73, v209, v68, s[20:21]
	v_add_f32_e32 v68, v75, v91
	s_waitcnt lgkmcnt(6)
	v_add_f32_e32 v68, v68, v248
	v_cndmask_b32_e64 v72, v209, v68, s[22:23]
	v_add_f32_e32 v68, v76, v92
	s_waitcnt lgkmcnt(5)
	v_add_f32_e32 v68, v68, v249
	v_cndmask_b32_e64 v75, v209, v68, s[24:25]
	v_add_f32_e32 v68, v77, v93
	s_waitcnt lgkmcnt(4)
	v_add_f32_e32 v68, v68, v250
	v_cndmask_b32_e64 v74, v209, v68, s[26:27]
	v_add_f32_e32 v68, v78, v94
	s_waitcnt lgkmcnt(3)
	v_add_f32_e32 v68, v68, v251
	v_cndmask_b32_e64 v77, v209, v68, s[28:29]
	v_add_f32_e32 v68, v79, v95
	s_waitcnt lgkmcnt(2)
	v_add_f32_e32 v68, v68, v252
	v_cndmask_b32_e64 v76, v209, v68, s[30:31]
	v_add_f32_e32 v68, v80, v96
	s_waitcnt lgkmcnt(1)
	v_add_f32_e32 v68, v68, v253
	v_cndmask_b32_e64 v79, v209, v68, s[34:35]
	v_add_f32_e32 v68, v81, v97
	s_waitcnt lgkmcnt(0)
	v_add_f32_e32 v68, v68, v254
	v_cndmask_b32_e64 v78, v209, v68, s[36:37]
	v_max_f32_e32 v68, v153, v153
	v_max_f32_e32 v80, v185, v185
	v_max_f32_e32 v68, v80, v68
	v_max3_f32 v68, v68, v99, v98
	v_max3_f32 v68, v68, v101, v100
	v_max3_f32 v68, v68, v103, v102
	v_max3_f32 v68, v68, v105, v104
	v_max3_f32 v68, v68, v107, v106
	v_max3_f32 v68, v68, v109, v108
	v_max3_f32 v68, v68, v111, v110
	v_max3_f32 v68, v68, v113, v112
	v_max3_f32 v68, v68, v67, v66
	v_max3_f32 v68, v68, v82, v69
	v_max3_f32 v68, v68, v71, v70
	v_max3_f32 v68, v68, v73, v72
	v_max3_f32 v68, v68, v75, v74
	v_max3_f32 v68, v68, v77, v76
	v_max3_f32 v68, v68, v79, v78
	v_mov_b32_e32 v80, v68
	s_nop 1
	v_permlane32_swap_b32_e32 v68, v80
	v_max3_f32 v68, v184, v68, v80
	v_sub_f32_e32 v80, v184, v68
	v_mul_f32_e32 v80, 0x3e0293ee, v80
	v_exp_f32_e32 v80, v80
	s_nop 0
	v_cmp_gt_f32_e32 vcc, 1.0, v80
	s_mov_b32 s32, 0
	s_cbranch_vccz .LBB0_438
	s_mov_b32 s32, 1
	s_and_saveexec_b64 s[88:89], s[38:39]
	ds_write_b32 v157, v80 offset:34816
	s_or_b64 exec, exec, s[88:89]
	s_waitcnt lgkmcnt(0)
	v_add_u32_e32 v81, v156, v0
	ds_read_b128 v[118:121], v81 offset:34912
	ds_read_b128 v[122:125], v81 offset:34880
	ds_read_b128 v[126:129], v81 offset:34848
	ds_read_b128 v[114:117], v81 offset:34816
